# added one static s_setprio 1 for waves 4-7 during the GEMM phases
# baseline (speedup 1.0000x reference)
; __device__ __forceinline__ int fresh_lane() { int l; asm volatile("v_mbcnt_lo_u32_b32 %0, -1, 0\n\tv_mbcnt_hi_u32_b32 %0, -1, %0" : "=v"(l)); return l; }
;     __host__ __device__ bool next(int i, Unit& u) const { return map((long)i * G + c, u); }
;     __host__ __device__ bool next(int i, Unit& u) const { if (i > 0) return false; const int x = c & 7, j = c >> 3; u.pm = 16 * s + 4 * (x >> 1) + (j & 3); u.pn = 8 * (x & 1) + (j >> 2); return true; }
;     __host__ __device__ bool next(int i, Unit& u) const { const bool ok = StaticOrder::next(i, u); u.pm &= mm; u.pn &= mn; return ok; }
; template <class Epi, class Sched, bool ALIGN_EPI = false, bool SP2 = false>
; __device__ __forceinline__ void gemm_phase(PG8_LAS unsigned char* lds, const Gemm g, const Sched& S, const Epi& E, int wid) {
;     const int lane = fresh_lane(), tid = wid * 64 + lane, wr = wid >> 2, wc = wid & 3, fr = lane & 15, fq = lane >> 4;
;     ...
;     for (;;) {
;         const bool has_next = S.next(ui + 1, nxt);
;         const char* nA = has_next ? (const char*)g.A + (size_t)nxt.pm * tstepA : cA; const char* nB = has_next ? (const char*)g.Bt + (size_t)nxt.pn * tstepB : cB;
;         for (int t = 0; t < nt; t += 2) {
.LBB0_226:
	s_cmp_ge_u32 s28, 4
	s_cbranch_scc0 .Lprio_skip_226
	s_setprio 1

; #define PG8_WAIT_V(n) asm volatile("s_waitcnt vmcnt(" #n ")" ::: "memory")
; #define PG8_BAR __builtin_amdgcn_s_barrier()
; template <class Epi, class Sched, bool ALIGN_EPI = false, bool SP2 = false>
; __device__ __forceinline__ void gemm_phase(PG8_LAS unsigned char* lds, const Gemm g, const Sched& S, const Epi& E, int wid) {
;     ...
;     PG8_WAIT_V(0);
;     if constexpr (!ALIGN_EPI) { if (wr == 0) PG8_BAR; }
;     PG8_BAR;
.LBB0_239:
	s_setprio 0
	s_waitcnt vmcnt(0)
	s_barrier

; #define PG8_WAIT_V(n) asm volatile("s_waitcnt vmcnt(" #n ")" ::: "memory")
; #define PG8_BAR __builtin_amdgcn_s_barrier()
; #define GRID_BAR() xcd_barrier(bar)
; #define GRID_BAR() do { } while (0)
; #define BOTH(k) (IN(k) && IN((k) + 1))
; template <class Epi, class Sched, bool ALIGN_EPI = false, bool SP2 = false>
; __device__ __forceinline__ void gemm_phase(PG8_LAS unsigned char* lds, const Gemm g, const Sched& S, const Epi& E, int wid) {
;     ...
;     PG8_WAIT_V(0);
;     if constexpr (!ALIGN_EPI) { if (wr == 0) PG8_BAR; }
;     PG8_BAR;
; __global__ void __launch_bounds__(NWAVES * 64, 2) fwd(Args args) {
;     ...
;         if (BOTH(2)) GRID_BAR();
;     }
;     if (IN(3)) {
.LBB0_339:
	s_setprio 0
	s_waitcnt vmcnt(0)
	s_barrier
	s_cmp_lt_i32 s97, 4
	s_cbranch_scc1 .LBB0_399
	s_branch .LBB0_344

; #define PG8_WAIT_V(n) asm volatile("s_waitcnt vmcnt(" #n ")" ::: "memory")
; #define PG8_BAR __builtin_amdgcn_s_barrier()
; #define GRID_BAR() xcd_barrier(bar)
; #define GRID_BAR() do { } while (0)
; #define BOTH(k) (IN(k) && IN((k) + 1))
; template <class Epi, class Sched, bool ALIGN_EPI = false, bool SP2 = false>
; __device__ __forceinline__ void gemm_phase(PG8_LAS unsigned char* lds, const Gemm g, const Sched& S, const Epi& E, int wid) {
;     ...
;     PG8_WAIT_V(0);
;     if constexpr (!ALIGN_EPI) { if (wr == 0) PG8_BAR; }
;     PG8_BAR;
; __global__ void __launch_bounds__(NWAVES * 64, 2) fwd(Args args) {
;     ...
;         if (BOTH(7)) GRID_BAR();
;     }
;     if (IN(8)) {
.LBB0_1059:
	s_setprio 0
	s_waitcnt vmcnt(0)
	s_barrier
	s_cmp_lt_i32 s97, 9
	s_cbranch_scc1 .LBB0_1119
	s_branch .LBB0_1064
